# drain norm_store's stores to 8 outstanding before issuing the 18 q-projection weight loads (caps per-wave outstanding VMEM)
# baseline (speedup 1.0000x reference)
; #define LAS __attribute__((address_space(3)))
; __device__ __forceinline__ unsigned pk2(float lo, float hi) { unsigned r; asm("v_cvt_pk_bf16_f32 %0, %1, %2" : "=v"(r) : "v"(lo), "v"(hi)); return r; }
; __device__ __forceinline__ float bf_lo(unsigned w) { return __uint_as_float(w << 16); }
; __device__ __forceinline__ float bf_hi(unsigned w) { return __uint_as_float(w & 0xffff0000u); }
; __device__ __forceinline__ float rsq(float x) { return __builtin_amdgcn_rsqf(x); }
; template <int NNT>
; __device__ __forceinline__ void norm_store(const f32x4 (&acc)[8][NNT], const LAS float* part, bf16_t* dst, int fr) {
; #pragma unroll
;     for (int mt = 0; mt < 8; ++mt) {
;         const LAS f32x4* pp = (const LAS f32x4*)(part + (16 * mt + fr) * 8); const f32x4 a = pp[0], b = pp[1];
;         const float rs = rsq((((a[0] + a[1]) + (a[2] + a[3])) + ((b[0] + b[1]) + (b[2] + b[3]))) * (1.0f / 256.0f) + EPS);
; #pragma unroll
;         for (int nt = 0; nt < NNT; ++nt) { u32x2 o; o.x = pk2(acc[mt][nt][0] * rs, acc[mt][nt][1] * rs); o.y = pk2(acc[mt][nt][2] * rs, acc[mt][nt][3] * rs);
;             *(u32x2*)(dst + (size_t)(16 * mt) * DM + 16 * nt) = o; }
;     }
; }
; __device__ __forceinline__ void mixer_chunk(KP p, LAS unsigned char* lds, int l, int chunk) {
;     ...
;         const int row = c0 + 16 * w + fr, spos = s0 + 16 * w + fr;
;         const bf16_t* zr = zb + (size_t)row * DIN_P; const float* rt = (const float*)(ws + OFF_ROPE) + (size_t)row * 32;
;         const u32x2 r1 = *(const u32x2*)(zr + ZC_KR + 4 * fq), r2 = *(const u32x2*)(zr + ZC_KR + 16 + 4 * fq);
;         const f32x4 cs = *(const f32x4*)(rt + 4 * fq), sn = *(const f32x4*)(rt + 16 + 4 * fq);
;         const f32x4 k1 = (f32x4){bf_lo(r1.x), bf_hi(r1.x), bf_lo(r1.y), bf_hi(r1.y)}, k2 = (f32x4){bf_lo(r2.x), bf_hi(r2.x), bf_lo(r2.y), bf_hi(r2.y)};
;         const f32x4 o1 = k1 * cs - k2 * sn, o2 = k2 * cs + k1 * sn;
;         u32x2 ro1, ro2; ro1.x = pk2(o1[0], o1[1]); ro1.y = pk2(o1[2], o1[3]); ro2.x = pk2(o2[0], o2[1]); ro2.y = pk2(o2[2], o2[3]);
;         bf16_t* kd = (bf16_t*)(ws + OFF_K) + ((size_t)(bidx * 4) * SEQ + spos) * 96 + 64 + 4 * fq;
; #pragma unroll
;         for (int h = 0; h < 4; ++h) { *(u32x2*)(kd + (size_t)h * SEQ * 96) = ro1; *(u32x2*)(kd + (size_t)h * SEQ * 96 + 16) = ro2; }
;     }
;     __syncthreads();
;     norm_store<2>(accc, part0, mrow + 0 + 32 * w, fr);
.LBB0_316:
	s_or_b64 exec, exec, s[6:7]
	v_or_b32_e32 v168, s25, v217
	v_ashrrev_i32_e32 v169, 31, v168
	v_readlane_b32 s6, v252, 6
	v_lshlrev_b64 v[70:71], 11, v[168:169]
	v_readlane_b32 s7, v252, 7
	v_mov_b32_e32 v67, v1
	s_add_i32 s89, s88, s25
	v_lshl_add_u64 v[70:71], s[6:7], 0, v[70:71]
	v_lshl_add_u64 v[170:171], v[70:71], 0, v[66:67]
	v_or_b32_e32 v70, s89, v217
	s_add_i32 s6, s88, s24
	v_ashrrev_i32_e32 v71, 31, v70
	s_waitcnt lgkmcnt(0)
	v_mov_b64_e32 v[72:73], s[44:45]
	v_or_b32_e32 v76, s6, v217
	v_mad_i64_i32 v[72:73], s[6:7], v70, s65, v[72:73]
	v_lshlrev_b64 v[70:71], 7, v[70:71]
	v_lshlrev_b32_e32 v221, 2, v68
	v_lshl_add_u64 v[70:71], s[92:93], 0, v[70:71]
	v_lshl_add_u64 v[72:73], v[72:73], 0, v[66:67]
	v_lshlrev_b32_e32 v68, 4, v68
	v_mov_b32_e32 v69, v1
	global_load_dwordx2 v[78:79], v[72:73], off offset:1664
	global_load_dwordx2 v[80:81], v[72:73], off offset:1696
	v_lshl_add_u64 v[72:73], v[70:71], 0, v[68:69]
	global_load_dwordx4 v[68:71], v[72:73], off
	s_nop 0
	global_load_dwordx4 v[72:75], v[72:73], off offset:64
	s_ashr_i32 s6, s23, 3
	s_and_b32 s96, s6, -4
	s_ashr_i32 s97, s96, 31
	s_lshl_b64 s[6:7], s[96:97], 12
	v_ashrrev_i32_e32 v77, 31, v76
	s_ashr_i32 s43, s42, 31
	s_cmp_eq_u32 s46, 0
	s_waitcnt vmcnt(3)
	v_lshlrev_b32_e32 v82, 16, v78
	s_waitcnt vmcnt(2)
	v_lshlrev_b32_e32 v84, 16, v80
	v_and_b32_e32 v85, 0xffff0000, v80
	v_lshlrev_b32_e32 v80, 16, v81
	v_and_b32_e32 v81, 0xffff0000, v81
	v_and_b32_e32 v83, 0xffff0000, v78
	v_lshlrev_b32_e32 v78, 16, v79
	v_and_b32_e32 v79, 0xffff0000, v79
	s_waitcnt vmcnt(0)
	v_pk_mul_f32 v[86:87], v[74:75], v[80:81]
	v_pk_mul_f32 v[88:89], v[72:73], v[84:85]
	v_pk_fma_f32 v[86:87], v[70:71], v[78:79], v[86:87] neg_lo:[0,0,1] neg_hi:[0,0,1]
	v_pk_fma_f32 v[88:89], v[68:69], v[82:83], v[88:89] neg_lo:[0,0,1] neg_hi:[0,0,1]
	v_pk_mul_f32 v[70:71], v[70:71], v[80:81]
	v_pk_mul_f32 v[68:69], v[68:69], v[84:85]
	v_pk_fma_f32 v[70:71], v[74:75], v[78:79], v[70:71]
	v_pk_fma_f32 v[68:69], v[72:73], v[82:83], v[68:69]
	v_mov_b64_e32 v[74:75], s[12:13]
	v_cvt_pk_bf16_f32 v68, v68, v69
	v_cvt_pk_bf16_f32 v69, v70, v71
	v_lshl_add_u64 v[70:71], s[6:7], 0, v[76:77]
	v_mad_u64_u32 v[74:75], s[6:7], v70, s57, v[74:75]
	v_mad_i32_i24 v75, v71, s57, v75
	v_lshl_add_u64 v[66:67], v[74:75], 0, v[66:67]
	s_mov_b32 s6, 0xc0000
	v_add_co_u32_e32 v70, vcc, s6, v66
	v_cvt_pk_bf16_f32 v72, v88, v89
	v_cvt_pk_bf16_f32 v73, v86, v87
	s_mov_b32 s6, 0x180000
	s_nop 0
	v_addc_co_u32_e32 v71, vcc, 0, v67, vcc
	global_store_dwordx2 v[66:67], v[72:73], off offset:128
	global_store_dwordx2 v[66:67], v[68:69], off offset:160
	global_store_dwordx2 v[70:71], v[72:73], off offset:128
	global_store_dwordx2 v[70:71], v[68:69], off offset:160
	v_add_co_u32_e32 v70, vcc, s6, v66
	s_mov_b32 s6, 0x240000
	s_nop 0
	v_addc_co_u32_e32 v71, vcc, 0, v67, vcc
	v_add_co_u32_e32 v66, vcc, s6, v66
	global_store_dwordx2 v[70:71], v[72:73], off offset:128
	global_store_dwordx2 v[70:71], v[68:69], off offset:160
	v_addc_co_u32_e32 v67, vcc, 0, v67, vcc
	global_store_dwordx2 v[66:67], v[72:73], off offset:128
	global_store_dwordx2 v[66:67], v[68:69], off offset:160
	s_barrier
	ds_read_b128 v[68:71], v215
	ds_read_b128 v[72:75], v215 offset:16
	v_lshl_add_u64 v[66:67], s[42:43], 1, v[170:171]
	s_mov_b32 s6, 0x8000
	s_cselect_b64 s[42:43], -1, 0
	s_waitcnt lgkmcnt(1)
	v_mov_b32_e32 v76, v68
	s_waitcnt lgkmcnt(0)
	v_mov_b32_e32 v77, v72
	v_mov_b32_e32 v72, v69
	v_pk_add_f32 v[68:69], v[76:77], v[72:73]
	v_mov_b32_e32 v72, v70
	v_mov_b32_e32 v73, v74
	v_mov_b32_e32 v74, v71
	v_pk_add_f32 v[70:71], v[72:73], v[74:75]
	s_cmp_lg_u32 s46, 0
	v_pk_add_f32 v[68:69], v[68:69], v[70:71]
	s_cselect_b64 s[90:91], -1, 0
	v_add_f32_e32 v68, v68, v69
	v_fmamk_f32 v68, v68, 0x3b800000, v189
	v_rsq_f32_e32 v68, v68
	s_nop 0
	v_mul_f32_e32 v62, v62, v68
	v_mul_f32_e32 v63, v63, v68
	v_mul_f32_e32 v58, v58, v68
	v_mul_f32_e32 v59, v59, v68
	v_cvt_pk_bf16_f32 v62, v62, v63
	v_mul_f32_e32 v63, v64, v68
	v_cvt_pk_bf16_f32 v58, v58, v59
	v_mul_f32_e32 v59, v60, v68
	v_mul_f32_e32 v64, v65, v68
	v_cvt_pk_bf16_f32 v63, v63, v64
	global_store_dwordx2 v[66:67], v[62:63], off
	v_mul_f32_e32 v60, v61, v68
	v_cvt_pk_bf16_f32 v59, v59, v60
	global_store_dwordx2 v[66:67], v[58:59], off offset:32
	ds_read_b128 v[58:61], v215 offset:512
	ds_read_b128 v[62:65], v215 offset:528
	s_waitcnt lgkmcnt(1)
	v_mov_b32_e32 v68, v58
	s_waitcnt lgkmcnt(0)
	v_mov_b32_e32 v69, v62
	v_mov_b32_e32 v62, v59
	v_pk_add_f32 v[58:59], v[68:69], v[62:63]
	v_mov_b32_e32 v62, v60
	v_mov_b32_e32 v63, v64
	v_mov_b32_e32 v64, v61
	v_pk_add_f32 v[60:61], v[62:63], v[64:65]
	s_nop 0
	v_pk_add_f32 v[58:59], v[58:59], v[60:61]
	s_nop 0
	v_add_f32_e32 v58, v58, v59
	v_fmamk_f32 v58, v58, 0x3b800000, v189
	v_rsq_f32_e32 v58, v58
	s_nop 0
	v_mul_f32_e32 v54, v54, v58
	v_mul_f32_e32 v55, v55, v58
	v_cvt_pk_bf16_f32 v54, v54, v55
	v_mul_f32_e32 v55, v56, v58
	v_mul_f32_e32 v56, v57, v58
	v_cvt_pk_bf16_f32 v55, v55, v56
	v_add_co_u32_e32 v56, vcc, s6, v66
	v_mul_f32_e32 v50, v50, v58
	v_mul_f32_e32 v51, v51, v58
	v_addc_co_u32_e32 v57, vcc, 0, v67, vcc
	v_cvt_pk_bf16_f32 v50, v50, v51
	v_mul_f32_e32 v51, v52, v58
	global_store_dwordx2 v[56:57], v[54:55], off
	v_mul_f32_e32 v52, v53, v58
	v_cvt_pk_bf16_f32 v51, v51, v52
	global_store_dwordx2 v[56:57], v[50:51], off offset:32
	ds_read_b128 v[50:53], v215 offset:1024
	ds_read_b128 v[54:57], v215 offset:1040
	s_mov_b32 s6, 0x18000
	s_waitcnt lgkmcnt(1)
	v_mov_b32_e32 v58, v50
	s_waitcnt lgkmcnt(0)
; #define LAS __attribute__((address_space(3)))
; __device__ __forceinline__ unsigned pk2(float lo, float hi) { unsigned r; asm("v_cvt_pk_bf16_f32 %0, %1, %2" : "=v"(r) : "v"(lo), "v"(hi)); return r; }
; __device__ __forceinline__ float rsq(float x) { return __builtin_amdgcn_rsqf(x); }
; template <int NNT>
; __device__ __forceinline__ void norm_store(const f32x4 (&acc)[8][NNT], const LAS float* part, bf16_t* dst, int fr) {
; #pragma unroll
;     for (int mt = 0; mt < 8; ++mt) {
;         const LAS f32x4* pp = (const LAS f32x4*)(part + (16 * mt + fr) * 8); const f32x4 a = pp[0], b = pp[1];
;         const float rs = rsq((((a[0] + a[1]) + (a[2] + a[3])) + ((b[0] + b[1]) + (b[2] + b[3]))) * (1.0f / 256.0f) + EPS);
; #pragma unroll
;         for (int nt = 0; nt < NNT; ++nt) { u32x2 o; o.x = pk2(acc[mt][nt][0] * rs, acc[mt][nt][1] * rs); o.y = pk2(acc[mt][nt][2] * rs, acc[mt][nt][3] * rs);
;             *(u32x2*)(dst + (size_t)(16 * mt) * DM + 16 * nt) = o; }
;     }
; }
	v_mov_b32_e32 v59, v54
	v_mov_b32_e32 v54, v51
	v_pk_add_f32 v[50:51], v[58:59], v[54:55]
	v_mov_b32_e32 v54, v52
	v_mov_b32_e32 v55, v56
	v_mov_b32_e32 v56, v53
	v_pk_add_f32 v[52:53], v[54:55], v[56:57]
	s_nop 0
	v_pk_add_f32 v[50:51], v[50:51], v[52:53]
	s_nop 0
	v_add_f32_e32 v50, v50, v51
	v_fmamk_f32 v50, v50, 0x3b800000, v189
	v_rsq_f32_e32 v50, v50
	s_nop 0
	v_mul_f32_e32 v46, v46, v50
	v_mul_f32_e32 v47, v47, v50
	v_cvt_pk_bf16_f32 v46, v46, v47
	v_mul_f32_e32 v47, v48, v50
	v_mul_f32_e32 v48, v49, v50
	v_cvt_pk_bf16_f32 v47, v47, v48
	v_add_co_u32_e32 v48, vcc, s72, v66
	v_mul_f32_e32 v42, v42, v50
	v_mul_f32_e32 v43, v43, v50
	v_addc_co_u32_e32 v49, vcc, 0, v67, vcc
	v_cvt_pk_bf16_f32 v42, v42, v43
	v_mul_f32_e32 v43, v44, v50
	global_store_dwordx2 v[48:49], v[46:47], off
	v_mul_f32_e32 v44, v45, v50
	v_cvt_pk_bf16_f32 v43, v43, v44
	global_store_dwordx2 v[48:49], v[42:43], off offset:32
	ds_read_b128 v[42:45], v215 offset:1536
	ds_read_b128 v[46:49], v215 offset:1552
	s_waitcnt lgkmcnt(1)
	v_mov_b32_e32 v50, v42
	s_waitcnt lgkmcnt(0)
	v_mov_b32_e32 v51, v46
	v_mov_b32_e32 v46, v43
	v_pk_add_f32 v[42:43], v[50:51], v[46:47]
	v_mov_b32_e32 v46, v44
	v_mov_b32_e32 v47, v48
	v_mov_b32_e32 v48, v45
	v_pk_add_f32 v[44:45], v[46:47], v[48:49]
	s_nop 0
	v_pk_add_f32 v[42:43], v[42:43], v[44:45]
	s_nop 0
	v_add_f32_e32 v42, v42, v43
	v_fmamk_f32 v42, v42, 0x3b800000, v189
	v_rsq_f32_e32 v42, v42
	s_nop 0
	v_mul_f32_e32 v38, v38, v42
	v_mul_f32_e32 v39, v39, v42
	v_cvt_pk_bf16_f32 v38, v38, v39
	v_mul_f32_e32 v39, v40, v42
	v_mul_f32_e32 v40, v41, v42
	v_cvt_pk_bf16_f32 v39, v39, v40
	v_add_co_u32_e32 v40, vcc, s6, v66
	v_mul_f32_e32 v34, v34, v42
	v_mul_f32_e32 v35, v35, v42
	v_addc_co_u32_e32 v41, vcc, 0, v67, vcc
	v_cvt_pk_bf16_f32 v34, v34, v35
	v_mul_f32_e32 v35, v36, v42
	global_store_dwordx2 v[40:41], v[38:39], off
	v_mul_f32_e32 v36, v37, v42
	v_cvt_pk_bf16_f32 v35, v35, v36
	global_store_dwordx2 v[40:41], v[34:35], off offset:32
	ds_read_b128 v[34:37], v215 offset:2048
	ds_read_b128 v[38:41], v215 offset:2064
	s_mov_b32 s6, 0x20000
	s_waitcnt lgkmcnt(1)
	v_mov_b32_e32 v42, v34
	s_waitcnt lgkmcnt(0)
	v_mov_b32_e32 v43, v38
	v_mov_b32_e32 v38, v35
	v_pk_add_f32 v[34:35], v[42:43], v[38:39]
	v_mov_b32_e32 v38, v36
	v_mov_b32_e32 v39, v40
	v_mov_b32_e32 v40, v37
	v_pk_add_f32 v[36:37], v[38:39], v[40:41]
	s_nop 0
	v_pk_add_f32 v[34:35], v[34:35], v[36:37]
	s_nop 0
	v_add_f32_e32 v34, v34, v35
	v_fmamk_f32 v34, v34, 0x3b800000, v189
	v_rsq_f32_e32 v34, v34
	s_nop 0
	v_mul_f32_e32 v30, v30, v34
	v_mul_f32_e32 v31, v31, v34
	v_cvt_pk_bf16_f32 v30, v30, v31
	v_mul_f32_e32 v31, v32, v34
	v_mul_f32_e32 v32, v33, v34
	v_cvt_pk_bf16_f32 v31, v31, v32
	v_add_co_u32_e32 v32, vcc, s6, v66
	v_mul_f32_e32 v26, v26, v34
	v_mul_f32_e32 v27, v27, v34
	v_addc_co_u32_e32 v33, vcc, 0, v67, vcc
	v_cvt_pk_bf16_f32 v26, v26, v27
	v_mul_f32_e32 v27, v28, v34
	global_store_dwordx2 v[32:33], v[30:31], off
	v_mul_f32_e32 v28, v29, v34
	v_cvt_pk_bf16_f32 v27, v27, v28
	global_store_dwordx2 v[32:33], v[26:27], off offset:32
	ds_read_b128 v[26:29], v215 offset:2560
	ds_read_b128 v[30:33], v215 offset:2576
	s_mov_b32 s6, 0x28000
	s_waitcnt lgkmcnt(1)
	v_mov_b32_e32 v34, v26
	s_waitcnt lgkmcnt(0)
	v_mov_b32_e32 v35, v30
	v_mov_b32_e32 v30, v27
	v_pk_add_f32 v[26:27], v[34:35], v[30:31]
	v_mov_b32_e32 v30, v28
	v_mov_b32_e32 v31, v32
	v_mov_b32_e32 v32, v29
	v_pk_add_f32 v[28:29], v[30:31], v[32:33]
	s_nop 0
	v_pk_add_f32 v[26:27], v[26:27], v[28:29]
	s_nop 0
	v_add_f32_e32 v26, v26, v27
	v_fmamk_f32 v26, v26, 0x3b800000, v189
	v_rsq_f32_e32 v26, v26
	s_nop 0
	v_mul_f32_e32 v22, v22, v26
	v_mul_f32_e32 v23, v23, v26
	v_cvt_pk_bf16_f32 v22, v22, v23
	v_mul_f32_e32 v23, v24, v26
	v_mul_f32_e32 v24, v25, v26
	v_cvt_pk_bf16_f32 v23, v23, v24
	v_add_co_u32_e32 v24, vcc, s6, v66
	v_mul_f32_e32 v18, v18, v26
	v_mul_f32_e32 v19, v19, v26
	v_addc_co_u32_e32 v25, vcc, 0, v67, vcc
	v_cvt_pk_bf16_f32 v18, v18, v19
	v_mul_f32_e32 v19, v20, v26
	global_store_dwordx2 v[24:25], v[22:23], off
	v_mul_f32_e32 v20, v21, v26
	v_cvt_pk_bf16_f32 v19, v19, v20
	global_store_dwordx2 v[24:25], v[18:19], off offset:32
	ds_read_b128 v[18:21], v215 offset:3072
	ds_read_b128 v[22:25], v215 offset:3088
	s_mov_b32 s6, 0x30000
	s_waitcnt lgkmcnt(1)
	v_mov_b32_e32 v26, v18
	s_waitcnt lgkmcnt(0)
	v_mov_b32_e32 v27, v22
	v_mov_b32_e32 v22, v19
	v_pk_add_f32 v[18:19], v[26:27], v[22:23]
	v_mov_b32_e32 v22, v20
	v_mov_b32_e32 v23, v24
	v_mov_b32_e32 v24, v21
	v_pk_add_f32 v[20:21], v[22:23], v[24:25]
	s_nop 0
	v_pk_add_f32 v[18:19], v[18:19], v[20:21]
	s_nop 0
	v_add_f32_e32 v18, v18, v19
	v_fmamk_f32 v18, v18, 0x3b800000, v189
	v_rsq_f32_e32 v18, v18
	s_nop 0
	v_mul_f32_e32 v14, v14, v18
	v_mul_f32_e32 v15, v15, v18
	v_cvt_pk_bf16_f32 v14, v14, v15
	v_mul_f32_e32 v15, v16, v18
	v_mul_f32_e32 v16, v17, v18
	v_cvt_pk_bf16_f32 v15, v15, v16
	v_add_co_u32_e32 v16, vcc, s6, v66
	v_mul_f32_e32 v10, v10, v18
	v_mul_f32_e32 v11, v11, v18
	v_addc_co_u32_e32 v17, vcc, 0, v67, vcc
	v_cvt_pk_bf16_f32 v10, v10, v11
	v_mul_f32_e32 v11, v12, v18
	global_store_dwordx2 v[16:17], v[14:15], off
	v_mul_f32_e32 v12, v13, v18
	v_cvt_pk_bf16_f32 v11, v11, v12
	global_store_dwordx2 v[16:17], v[10:11], off offset:32
	ds_read_b128 v[10:13], v215 offset:3584
	ds_read_b128 v[14:17], v215 offset:3600
	s_mov_b32 s6, 0x38000
	s_waitcnt lgkmcnt(1)
	v_mov_b32_e32 v18, v10
	s_waitcnt lgkmcnt(0)
; #define LAS __attribute__((address_space(3)))
; __device__ __forceinline__ unsigned pk2(float lo, float hi) { unsigned r; asm("v_cvt_pk_bf16_f32 %0, %1, %2" : "=v"(r) : "v"(lo), "v"(hi)); return r; }
; __device__ __forceinline__ float rsq(float x) { return __builtin_amdgcn_rsqf(x); }
; template <int NKS, int NNT>
; __device__ __forceinline__ void wgemm(f32x4 (&acc)[8][NNT], const LAS bf16_t* A, const int lda, const bf16_t* Bp, const int ldb) {
;     u32x4 bf[NNT][NKS];
; #pragma unroll
;     for (int nt = 0; nt < NNT; ++nt) ldfr(bf[nt], Bp + (size_t)(16 * nt) * ldb);
; #pragma unroll
;     for (int nt = 0; nt < NNT; ++nt) pin(bf[nt]);
; #pragma unroll
;     for (int mt = 0; mt < 8; ++mt) {
;         bf16x8 af[NKS];
; #pragma unroll
;         for (int ks = 0; ks < NKS; ++ks) af[ks] = *(const LAS bf16x8*)(A + (16 * mt) * lda + 32 * ks);
; template <int NNT>
; __device__ __forceinline__ void norm_store(const f32x4 (&acc)[8][NNT], const LAS float* part, bf16_t* dst, int fr) {
; #pragma unroll
;     for (int mt = 0; mt < 8; ++mt) {
;         const LAS f32x4* pp = (const LAS f32x4*)(part + (16 * mt + fr) * 8); const f32x4 a = pp[0], b = pp[1];
;         const float rs = rsq((((a[0] + a[1]) + (a[2] + a[3])) + ((b[0] + b[1]) + (b[2] + b[3]))) * (1.0f / 256.0f) + EPS);
; #pragma unroll
;         for (int nt = 0; nt < NNT; ++nt) { u32x2 o; o.x = pk2(acc[mt][nt][0] * rs, acc[mt][nt][1] * rs); o.y = pk2(acc[mt][nt][2] * rs, acc[mt][nt][3] * rs);
;             *(u32x2*)(dst + (size_t)(16 * mt) * DM + 16 * nt) = o; }
;     }
; }
	v_mov_b32_e32 v19, v14
	v_mov_b32_e32 v14, v11
	v_pk_add_f32 v[10:11], v[18:19], v[14:15]
	v_mov_b32_e32 v14, v12
	v_mov_b32_e32 v15, v16
	v_mov_b32_e32 v16, v13
	v_pk_add_f32 v[12:13], v[14:15], v[16:17]
	s_nop 0
	v_pk_add_f32 v[10:11], v[10:11], v[12:13]
	s_nop 0
	v_add_f32_e32 v10, v10, v11
	v_fmamk_f32 v10, v10, 0x3b800000, v189
	v_rsq_f32_e32 v10, v10
	s_nop 0
	v_mul_f32_e32 v2, v2, v10
	v_mul_f32_e32 v3, v3, v10
	v_cvt_pk_bf16_f32 v2, v2, v3
	v_mul_f32_e32 v3, v4, v10
	v_mul_f32_e32 v4, v5, v10
	v_cvt_pk_bf16_f32 v3, v3, v4
	v_add_co_u32_e32 v4, vcc, s6, v66
	s_mul_i32 s6, s55, 48
	s_nop 0
	v_addc_co_u32_e32 v5, vcc, 0, v67, vcc
	global_store_dwordx2 v[4:5], v[2:3], off
	v_mul_f32_e32 v2, v6, v10
	v_mul_f32_e32 v3, v7, v10
	v_cvt_pk_bf16_f32 v2, v2, v3
	v_mul_f32_e32 v3, v8, v10
	v_mul_f32_e32 v6, v9, v10
	v_cvt_pk_bf16_f32 v3, v3, v6
	global_store_dwordx2 v[4:5], v[2:3], off offset:32
	v_mul_u32_u24_e32 v2, 0x190, v217
	v_add3_u32 v162, 0, v2, v0
	v_or_b32_e32 v4, s6, v217
	v_mov_b64_e32 v[2:3], s[10:11]
	s_movk_i32 s6, 0x180
	v_mad_i64_i32 v[2:3], s[6:7], v4, s6, v[2:3]
	v_lshl_add_u64 v[10:11], v[2:3], 0, v[0:1]
	s_movk_i32 s6, 0x1000
	v_add_co_u32_e32 v12, vcc, s6, v10
	s_waitcnt vmcnt(8)
	global_load_dwordx4 v[154:157], v[10:11], off
	global_load_dwordx4 v[150:153], v[10:11], off offset:64
	global_load_dwordx4 v[142:145], v[10:11], off offset:128
	global_load_dwordx4 v[138:141], v[10:11], off offset:192
	global_load_dwordx4 v[6:9], v[10:11], off offset:256
	global_load_dwordx4 v[2:5], v[10:11], off offset:320
	v_addc_co_u32_e32 v13, vcc, 0, v11, vcc
	v_add_co_u32_e32 v10, vcc, s68, v10
	global_load_dwordx4 v[22:25], v[12:13], off offset:2048
	global_load_dwordx4 v[98:101], v[12:13], off offset:2112
	global_load_dwordx4 v[102:105], v[12:13], off offset:2176
	global_load_dwordx4 v[106:109], v[12:13], off offset:2240
	global_load_dwordx4 v[110:113], v[12:13], off offset:2304
	global_load_dwordx4 v[114:117], v[12:13], off offset:2368
	v_addc_co_u32_e32 v11, vcc, 0, v11, vcc
	global_load_dwordx4 v[146:149], v[10:11], off
	global_load_dwordx4 v[118:121], v[10:11], off offset:64
	global_load_dwordx4 v[122:125], v[10:11], off offset:128
	global_load_dwordx4 v[126:129], v[10:11], off offset:192
	global_load_dwordx4 v[130:133], v[10:11], off offset:256
	global_load_dwordx4 v[134:137], v[10:11], off offset:320
	s_waitcnt vmcnt(12)
	s_waitcnt vmcnt(6)
	s_waitcnt vmcnt(0)
	ds_read_b128 v[10:13], v162
	ds_read_b128 v[14:17], v162 offset:64
	ds_read_b128 v[18:21], v162 offset:128
	ds_read_b128 v[26:29], v162 offset:192
	ds_read_b128 v[30:33], v162 offset:256
	ds_read_b128 v[34:37], v162 offset:320
	s_waitcnt lgkmcnt(5)
	v_mfma_f32_16x16x32_bf16 v[38:41], v[154:157], v[10:13], 0
	s_and_b64 vcc, exec, s[42:43]
	s_waitcnt lgkmcnt(4)
	v_mfma_f32_16x16x32_bf16 v[38:41], v[150:153], v[14:17], v[38:41]
	s_waitcnt lgkmcnt(3)
	v_mfma_f32_16x16x32_bf16 v[38:41], v[142:145], v[18:21], v[38:41]
	s_waitcnt lgkmcnt(2)
	v_mfma_f32_16x16x32_bf16 v[38:41], v[138:141], v[26:29], v[38:41]
	s_waitcnt lgkmcnt(1)
	v_mfma_f32_16x16x32_bf16 v[38:41], v[6:9], v[30:33], v[38:41]
	s_waitcnt lgkmcnt(0)
	v_mfma_f32_16x16x32_bf16 v[82:85], v[2:5], v[34:37], v[38:41]
	v_mfma_f32_16x16x32_bf16 v[38:41], v[22:25], v[10:13], 0
	v_mfma_f32_16x16x32_bf16 v[10:13], v[146:149], v[10:13], 0
	v_mfma_f32_16x16x32_bf16 v[38:41], v[98:101], v[14:17], v[38:41]
	v_mfma_f32_16x16x32_bf16 v[10:13], v[118:121], v[14:17], v[10:13]
	v_mfma_f32_16x16x32_bf16 v[38:41], v[102:105], v[18:21], v[38:41]
	v_mfma_f32_16x16x32_bf16 v[10:13], v[122:125], v[18:21], v[10:13]
	v_mfma_f32_16x16x32_bf16 v[38:41], v[106:109], v[26:29], v[38:41]
	v_mfma_f32_16x16x32_bf16 v[10:13], v[126:129], v[26:29], v[10:13]
	v_mfma_f32_16x16x32_bf16 v[38:41], v[110:113], v[30:33], v[38:41]
	v_mfma_f32_16x16x32_bf16 v[10:13], v[130:133], v[30:33], v[10:13]
	v_mfma_f32_16x16x32_bf16 v[90:93], v[114:117], v[34:37], v[38:41]
	v_mfma_f32_16x16x32_bf16 v[94:97], v[134:137], v[34:37], v[10:13]
	s_nop 5
	ds_read_b128 v[10:13], v162 offset:6400
	ds_read_b128 v[14:17], v162 offset:6464
	ds_read_b128 v[18:21], v162 offset:6528
	ds_read_b128 v[26:29], v162 offset:6592
	ds_read_b128 v[30:33], v162 offset:6656
	ds_read_b128 v[34:37], v162 offset:6720
	s_waitcnt lgkmcnt(5)
	v_mfma_f32_16x16x32_bf16 v[38:41], v[154:157], v[10:13], 0
	s_waitcnt lgkmcnt(4)
	v_mfma_f32_16x16x32_bf16 v[38:41], v[150:153], v[14:17], v[38:41]
	s_waitcnt lgkmcnt(3)
	v_mfma_f32_16x16x32_bf16 v[38:41], v[142:145], v[18:21], v[38:41]
	s_waitcnt lgkmcnt(2)
	v_mfma_f32_16x16x32_bf16 v[38:41], v[138:141], v[26:29], v[38:41]
	s_waitcnt lgkmcnt(1)
	v_mfma_f32_16x16x32_bf16 v[38:41], v[6:9], v[30:33], v[38:41]
	s_waitcnt lgkmcnt(0)
	v_mfma_f32_16x16x32_bf16 v[74:77], v[2:5], v[34:37], v[38:41]
	v_mfma_f32_16x16x32_bf16 v[38:41], v[22:25], v[10:13], 0
	v_mfma_f32_16x16x32_bf16 v[10:13], v[146:149], v[10:13], 0
	v_mfma_f32_16x16x32_bf16 v[38:41], v[98:101], v[14:17], v[38:41]
	v_mfma_f32_16x16x32_bf16 v[10:13], v[118:121], v[14:17], v[10:13]
	v_mfma_f32_16x16x32_bf16 v[38:41], v[102:105], v[18:21], v[38:41]
	v_mfma_f32_16x16x32_bf16 v[10:13], v[122:125], v[18:21], v[10:13]
	v_mfma_f32_16x16x32_bf16 v[38:41], v[106:109], v[26:29], v[38:41]
	v_mfma_f32_16x16x32_bf16 v[10:13], v[126:129], v[26:29], v[10:13]
	v_mfma_f32_16x16x32_bf16 v[38:41], v[110:113], v[30:33], v[38:41]
	v_mfma_f32_16x16x32_bf16 v[10:13], v[130:133], v[30:33], v[10:13]
	v_mfma_f32_16x16x32_bf16 v[78:81], v[114:117], v[34:37], v[38:41]
	v_mfma_f32_16x16x32_bf16 v[86:89], v[134:137], v[34:37], v[10:13]
	s_nop 5
	ds_read_b128 v[10:13], v162 offset:12800
	ds_read_b128 v[14:17], v162 offset:12864
	ds_read_b128 v[18:21], v162 offset:12928
	ds_read_b128 v[26:29], v162 offset:12992
	ds_read_b128 v[30:33], v162 offset:13056
	ds_read_b128 v[34:37], v162 offset:13120
	s_waitcnt lgkmcnt(5)
; #define LAS __attribute__((address_space(3)))
; __device__ __forceinline__ f32x4 mfma16(bf16x8 a, bf16x8 b, f32x4 c) { return __builtin_amdgcn_mfma_f32_16x16x32_bf16(a, b, c, 0, 0, 0); }
; template <int NKS, int NNT>
; __device__ __forceinline__ void wgemm(f32x4 (&acc)[8][NNT], const LAS bf16_t* A, const int lda, const bf16_t* Bp, const int ldb) {
;     u32x4 bf[NNT][NKS];
; #pragma unroll
;     for (int nt = 0; nt < NNT; ++nt) ldfr(bf[nt], Bp + (size_t)(16 * nt) * ldb);
; #pragma unroll
;     for (int nt = 0; nt < NNT; ++nt) pin(bf[nt]);
; #pragma unroll
;     for (int mt = 0; mt < 8; ++mt) {
;         bf16x8 af[NKS];
; #pragma unroll
;         for (int ks = 0; ks < NKS; ++ks) af[ks] = *(const LAS bf16x8*)(A + (16 * mt) * lda + 32 * ks);
; #pragma unroll
;         for (int nt = 0; nt < NNT; ++nt) { f32x4 a = (f32x4){0.f, 0.f, 0.f, 0.f};
; #pragma unroll
;             for (int ks = 0; ks < NKS; ++ks) a = mfma16(as_bf16x8(bf[nt][ks]), af[ks], a);
;             acc[mt][nt] = a; }
;     }
; }
	v_mfma_f32_16x16x32_bf16 v[38:41], v[154:157], v[10:13], 0
	s_waitcnt lgkmcnt(4)
	v_mfma_f32_16x16x32_bf16 v[38:41], v[150:153], v[14:17], v[38:41]
	s_waitcnt lgkmcnt(3)
	v_mfma_f32_16x16x32_bf16 v[38:41], v[142:145], v[18:21], v[38:41]
	s_waitcnt lgkmcnt(2)
	v_mfma_f32_16x16x32_bf16 v[38:41], v[138:141], v[26:29], v[38:41]
	s_waitcnt lgkmcnt(1)
	v_mfma_f32_16x16x32_bf16 v[38:41], v[6:9], v[30:33], v[38:41]
	s_waitcnt lgkmcnt(0)
	v_mfma_f32_16x16x32_bf16 v[62:65], v[2:5], v[34:37], v[38:41]
	v_mfma_f32_16x16x32_bf16 v[38:41], v[22:25], v[10:13], 0
	v_mfma_f32_16x16x32_bf16 v[10:13], v[146:149], v[10:13], 0
	v_mfma_f32_16x16x32_bf16 v[38:41], v[98:101], v[14:17], v[38:41]
	v_mfma_f32_16x16x32_bf16 v[10:13], v[118:121], v[14:17], v[10:13]
	v_mfma_f32_16x16x32_bf16 v[38:41], v[102:105], v[18:21], v[38:41]
	v_mfma_f32_16x16x32_bf16 v[10:13], v[122:125], v[18:21], v[10:13]
	v_mfma_f32_16x16x32_bf16 v[38:41], v[106:109], v[26:29], v[38:41]
	v_mfma_f32_16x16x32_bf16 v[10:13], v[126:129], v[26:29], v[10:13]
	v_mfma_f32_16x16x32_bf16 v[38:41], v[110:113], v[30:33], v[38:41]
	v_mfma_f32_16x16x32_bf16 v[10:13], v[130:133], v[30:33], v[10:13]
	v_mfma_f32_16x16x32_bf16 v[66:69], v[114:117], v[34:37], v[38:41]
	v_mfma_f32_16x16x32_bf16 v[70:73], v[134:137], v[34:37], v[10:13]
	s_nop 5
	ds_read_b128 v[10:13], v162 offset:19200
	ds_read_b128 v[14:17], v162 offset:19264
	ds_read_b128 v[18:21], v162 offset:19328
	ds_read_b128 v[26:29], v162 offset:19392
	ds_read_b128 v[30:33], v162 offset:19456
	ds_read_b128 v[34:37], v162 offset:19520
	s_waitcnt lgkmcnt(5)
	v_mfma_f32_16x16x32_bf16 v[38:41], v[154:157], v[10:13], 0
	s_waitcnt lgkmcnt(4)
	v_mfma_f32_16x16x32_bf16 v[38:41], v[150:153], v[14:17], v[38:41]
	s_waitcnt lgkmcnt(3)
	v_mfma_f32_16x16x32_bf16 v[38:41], v[142:145], v[18:21], v[38:41]
	s_waitcnt lgkmcnt(2)
	v_mfma_f32_16x16x32_bf16 v[38:41], v[138:141], v[26:29], v[38:41]
	s_waitcnt lgkmcnt(1)
	v_mfma_f32_16x16x32_bf16 v[38:41], v[6:9], v[30:33], v[38:41]
	s_waitcnt lgkmcnt(0)
	v_mfma_f32_16x16x32_bf16 v[50:53], v[2:5], v[34:37], v[38:41]
	v_mfma_f32_16x16x32_bf16 v[38:41], v[22:25], v[10:13], 0
	v_mfma_f32_16x16x32_bf16 v[10:13], v[146:149], v[10:13], 0
	v_mfma_f32_16x16x32_bf16 v[38:41], v[98:101], v[14:17], v[38:41]
	v_mfma_f32_16x16x32_bf16 v[10:13], v[118:121], v[14:17], v[10:13]
	v_mfma_f32_16x16x32_bf16 v[38:41], v[102:105], v[18:21], v[38:41]
	v_mfma_f32_16x16x32_bf16 v[10:13], v[122:125], v[18:21], v[10:13]
	v_mfma_f32_16x16x32_bf16 v[38:41], v[106:109], v[26:29], v[38:41]
	v_mfma_f32_16x16x32_bf16 v[10:13], v[126:129], v[26:29], v[10:13]
	v_mfma_f32_16x16x32_bf16 v[38:41], v[110:113], v[30:33], v[38:41]
	v_mfma_f32_16x16x32_bf16 v[10:13], v[130:133], v[30:33], v[10:13]
	v_mfma_f32_16x16x32_bf16 v[54:57], v[114:117], v[34:37], v[38:41]
	v_mfma_f32_16x16x32_bf16 v[58:61], v[134:137], v[34:37], v[10:13]
	s_nop 5
	ds_read_b128 v[10:13], v162 offset:25600
	ds_read_b128 v[14:17], v162 offset:25664
	ds_read_b128 v[18:21], v162 offset:25728
	ds_read_b128 v[26:29], v162 offset:25792
	ds_read_b128 v[34:37], v162 offset:25856
	ds_read_b128 v[42:45], v162 offset:25920
	s_waitcnt lgkmcnt(5)
	v_mfma_f32_16x16x32_bf16 v[30:33], v[154:157], v[10:13], 0
	v_mfma_f32_16x16x32_bf16 v[38:41], v[22:25], v[10:13], 0
	v_mfma_f32_16x16x32_bf16 v[10:13], v[146:149], v[10:13], 0
	s_waitcnt lgkmcnt(4)
	v_mfma_f32_16x16x32_bf16 v[30:33], v[150:153], v[14:17], v[30:33]
	v_mfma_f32_16x16x32_bf16 v[38:41], v[98:101], v[14:17], v[38:41]
	v_mfma_f32_16x16x32_bf16 v[10:13], v[118:121], v[14:17], v[10:13]
	s_waitcnt lgkmcnt(3)
	v_mfma_f32_16x16x32_bf16 v[30:33], v[142:145], v[18:21], v[30:33]
	v_mfma_f32_16x16x32_bf16 v[38:41], v[102:105], v[18:21], v[38:41]
	v_mfma_f32_16x16x32_bf16 v[10:13], v[122:125], v[18:21], v[10:13]
	s_waitcnt lgkmcnt(2)
	v_mfma_f32_16x16x32_bf16 v[30:33], v[138:141], v[26:29], v[30:33]
	v_mfma_f32_16x16x32_bf16 v[38:41], v[106:109], v[26:29], v[38:41]
	v_mfma_f32_16x16x32_bf16 v[10:13], v[126:129], v[26:29], v[10:13]
	s_waitcnt lgkmcnt(1)
	v_mfma_f32_16x16x32_bf16 v[30:33], v[6:9], v[34:37], v[30:33]
	v_mfma_f32_16x16x32_bf16 v[38:41], v[110:113], v[34:37], v[38:41]
	v_mfma_f32_16x16x32_bf16 v[10:13], v[130:133], v[34:37], v[10:13]
	s_waitcnt lgkmcnt(0)
	v_mfma_f32_16x16x32_bf16 v[30:33], v[2:5], v[42:45], v[30:33]
	v_mfma_f32_16x16x32_bf16 v[38:41], v[114:117], v[42:45], v[38:41]
	v_mfma_f32_16x16x32_bf16 v[46:49], v[134:137], v[42:45], v[10:13]
	s_nop 3
	ds_read_b128 v[10:13], v162 offset:32000
	ds_read_b128 v[14:17], v162 offset:32064
	ds_read_b128 v[18:21], v162 offset:32128
	ds_read_b128 v[42:45], v162 offset:32192
	ds_read_b128 v[158:161], v162 offset:32256
	ds_read_b128 v[172:175], v162 offset:32320
	s_waitcnt lgkmcnt(5)
	v_mfma_f32_16x16x32_bf16 v[26:29], v[154:157], v[10:13], 0
	v_mfma_f32_16x16x32_bf16 v[34:37], v[22:25], v[10:13], 0
	v_mfma_f32_16x16x32_bf16 v[10:13], v[146:149], v[10:13], 0
	s_waitcnt lgkmcnt(4)
	v_mfma_f32_16x16x32_bf16 v[26:29], v[150:153], v[14:17], v[26:29]
	v_mfma_f32_16x16x32_bf16 v[34:37], v[98:101], v[14:17], v[34:37]
	v_mfma_f32_16x16x32_bf16 v[10:13], v[118:121], v[14:17], v[10:13]
	s_waitcnt lgkmcnt(3)
	v_mfma_f32_16x16x32_bf16 v[26:29], v[142:145], v[18:21], v[26:29]
	v_mfma_f32_16x16x32_bf16 v[34:37], v[102:105], v[18:21], v[34:37]
	v_mfma_f32_16x16x32_bf16 v[10:13], v[122:125], v[18:21], v[10:13]
	s_waitcnt lgkmcnt(2)
	v_mfma_f32_16x16x32_bf16 v[26:29], v[138:141], v[42:45], v[26:29]
	v_mfma_f32_16x16x32_bf16 v[34:37], v[106:109], v[42:45], v[34:37]
	v_mfma_f32_16x16x32_bf16 v[10:13], v[126:129], v[42:45], v[10:13]
	s_waitcnt lgkmcnt(1)
; #define LAS __attribute__((address_space(3)))
; __device__ __forceinline__ f32x4 mfma16(bf16x8 a, bf16x8 b, f32x4 c) { return __builtin_amdgcn_mfma_f32_16x16x32_bf16(a, b, c, 0, 0, 0); }
; template <int NKS, int NNT>
; __device__ __forceinline__ void wgemm(f32x4 (&acc)[8][NNT], const LAS bf16_t* A, const int lda, const bf16_t* Bp, const int ldb) {
;     ...
;     for (int mt = 0; mt < 8; ++mt) {
;         bf16x8 af[NKS];
; #pragma unroll
;         for (int ks = 0; ks < NKS; ++ks) af[ks] = *(const LAS bf16x8*)(A + (16 * mt) * lda + 32 * ks);
; #pragma unroll
;         for (int nt = 0; nt < NNT; ++nt) { f32x4 a = (f32x4){0.f, 0.f, 0.f, 0.f};
; #pragma unroll
;             for (int ks = 0; ks < NKS; ++ks) a = mfma16(as_bf16x8(bf[nt][ks]), af[ks], a);
;             acc[mt][nt] = a; }
;     }
; }
; __device__ __forceinline__ void mixer_chunk(KP p, LAS unsigned char* lds, int l, int chunk) {
;     ...
;         const int head = (3 * w) / 6, d0 = 16 * ((3 * w) % 6);
;         u32x4 csn[16];
;         if (w & 1) {
; #pragma unroll
;             for (int mt = 0; mt < 8; ++mt) { const float* rt = (const float*)(ws + OFF_ROPE) + (size_t)(c0 + 16 * mt + fr) * 32 + 4 * fq; csn[2 * mt] = *(const u32x4*)rt; csn[2 * mt + 1] = *(const u32x4*)(rt + 16); }
;             pin(csn);
;         }
	v_mfma_f32_16x16x32_bf16 v[26:29], v[6:9], v[158:161], v[26:29]
	v_mfma_f32_16x16x32_bf16 v[34:37], v[110:113], v[158:161], v[34:37]
	v_mfma_f32_16x16x32_bf16 v[10:13], v[130:133], v[158:161], v[10:13]
	s_waitcnt lgkmcnt(0)
	v_mfma_f32_16x16x32_bf16 v[26:29], v[2:5], v[172:175], v[26:29]
	v_mfma_f32_16x16x32_bf16 v[34:37], v[114:117], v[172:175], v[34:37]
	v_mfma_f32_16x16x32_bf16 v[42:45], v[134:137], v[172:175], v[10:13]
	ds_read_b128 v[18:21], v162 offset:38400
	ds_read_b128 v[158:161], v162 offset:38464
	ds_read_b128 v[172:175], v162 offset:38528
	ds_read_b128 v[176:179], v162 offset:38592
	ds_read_b128 v[180:183], v162 offset:38656
	ds_read_b128 v[184:187], v162 offset:38720
	s_waitcnt lgkmcnt(5)
	v_mfma_f32_16x16x32_bf16 v[10:13], v[154:157], v[18:21], 0
	v_mfma_f32_16x16x32_bf16 v[14:17], v[22:25], v[18:21], 0
	v_mfma_f32_16x16x32_bf16 v[18:21], v[146:149], v[18:21], 0
	s_waitcnt lgkmcnt(4)
	v_mfma_f32_16x16x32_bf16 v[10:13], v[150:153], v[158:161], v[10:13]
	v_mfma_f32_16x16x32_bf16 v[14:17], v[98:101], v[158:161], v[14:17]
	v_mfma_f32_16x16x32_bf16 v[18:21], v[118:121], v[158:161], v[18:21]
	s_waitcnt lgkmcnt(3)
	v_mfma_f32_16x16x32_bf16 v[10:13], v[142:145], v[172:175], v[10:13]
	v_mfma_f32_16x16x32_bf16 v[14:17], v[102:105], v[172:175], v[14:17]
	v_mfma_f32_16x16x32_bf16 v[18:21], v[122:125], v[172:175], v[18:21]
	s_waitcnt lgkmcnt(2)
	v_mfma_f32_16x16x32_bf16 v[10:13], v[138:141], v[176:179], v[10:13]
	v_mfma_f32_16x16x32_bf16 v[14:17], v[106:109], v[176:179], v[14:17]
	v_mfma_f32_16x16x32_bf16 v[18:21], v[126:129], v[176:179], v[18:21]
	s_waitcnt lgkmcnt(1)
	v_mfma_f32_16x16x32_bf16 v[10:13], v[6:9], v[180:183], v[10:13]
	v_mfma_f32_16x16x32_bf16 v[14:17], v[110:113], v[180:183], v[14:17]
	v_mfma_f32_16x16x32_bf16 v[18:21], v[130:133], v[180:183], v[18:21]
	s_waitcnt lgkmcnt(0)
	v_mfma_f32_16x16x32_bf16 v[10:13], v[2:5], v[184:187], v[10:13]
	v_mfma_f32_16x16x32_bf16 v[14:17], v[114:117], v[184:187], v[14:17]
	v_mfma_f32_16x16x32_bf16 v[18:21], v[134:137], v[184:187], v[18:21]
	ds_read_b128 v[158:161], v162 offset:44800
	ds_read_b128 v[172:175], v162 offset:44864
	ds_read_b128 v[176:179], v162 offset:44928
	ds_read_b128 v[180:183], v162 offset:44992
	ds_read_b128 v[184:187], v162 offset:45056
	ds_read_b128 v[226:229], v162 offset:45120
	s_waitcnt lgkmcnt(5)
	v_mfma_f32_16x16x32_bf16 v[154:157], v[154:157], v[158:161], 0
	s_waitcnt lgkmcnt(4)
	v_mfma_f32_16x16x32_bf16 v[150:153], v[150:153], v[172:175], v[154:157]
	s_waitcnt lgkmcnt(3)
	v_mfma_f32_16x16x32_bf16 v[142:145], v[142:145], v[176:179], v[150:153]
	s_waitcnt lgkmcnt(2)
	v_mfma_f32_16x16x32_bf16 v[138:141], v[138:141], v[180:183], v[142:145]
	s_waitcnt lgkmcnt(1)
	v_mfma_f32_16x16x32_bf16 v[6:9], v[6:9], v[184:187], v[138:141]
	s_waitcnt lgkmcnt(0)
	v_mfma_f32_16x16x32_bf16 v[2:5], v[2:5], v[226:229], v[6:9]
	v_mfma_f32_16x16x32_bf16 v[6:9], v[22:25], v[158:161], 0
	v_mfma_f32_16x16x32_bf16 v[22:25], v[146:149], v[158:161], 0
	v_mfma_f32_16x16x32_bf16 v[6:9], v[98:101], v[172:175], v[6:9]
	v_mfma_f32_16x16x32_bf16 v[22:25], v[118:121], v[172:175], v[22:25]
	v_or_b32_e32 v174, 0x60, v168
	v_or_b32_e32 v172, 0x70, v168
	v_mfma_f32_16x16x32_bf16 v[6:9], v[102:105], v[176:179], v[6:9]
	v_mfma_f32_16x16x32_bf16 v[22:25], v[122:125], v[176:179], v[22:25]
	v_or_b32_e32 v178, 64, v168
	v_or_b32_e32 v176, 0x50, v168
	v_mfma_f32_16x16x32_bf16 v[6:9], v[106:109], v[180:183], v[6:9]
	v_mfma_f32_16x16x32_bf16 v[22:25], v[126:129], v[180:183], v[22:25]
	v_or_b32_e32 v182, 32, v168
	v_or_b32_e32 v180, 48, v168
	v_mfma_f32_16x16x32_bf16 v[6:9], v[110:113], v[184:187], v[6:9]
	v_mfma_f32_16x16x32_bf16 v[22:25], v[130:133], v[184:187], v[22:25]
	v_or_b32_e32 v184, 16, v168
	v_mfma_f32_16x16x32_bf16 v[6:9], v[114:117], v[226:229], v[6:9]
	v_mfma_f32_16x16x32_bf16 v[22:25], v[134:137], v[226:229], v[22:25]
	s_cbranch_vccnz .LBB0_318
	v_lshlrev_b32_e32 v98, 2, v221
	v_mov_b32_e32 v99, v1
	v_lshl_add_u64 v[98:99], s[92:93], 0, v[98:99]
	v_lshlrev_b64 v[100:101], 7, v[168:169]
	v_lshl_add_u64 v[100:101], v[98:99], 0, v[100:101]
	v_ashrrev_i32_e32 v185, 31, v184
	global_load_dwordx4 v[158:161], v[100:101], off
	global_load_dwordx4 v[154:157], v[100:101], off offset:64
	v_lshlrev_b64 v[100:101], 7, v[184:185]
	v_lshl_add_u64 v[100:101], v[98:99], 0, v[100:101]
	v_ashrrev_i32_e32 v183, 31, v182
	global_load_dwordx4 v[150:153], v[100:101], off
	global_load_dwordx4 v[146:149], v[100:101], off offset:64
	v_lshlrev_b64 v[100:101], 7, v[182:183]
	v_lshl_add_u64 v[100:101], v[98:99], 0, v[100:101]
	v_ashrrev_i32_e32 v181, 31, v180
	global_load_dwordx4 v[142:145], v[100:101], off
	global_load_dwordx4 v[138:141], v[100:101], off offset:64
	v_lshlrev_b64 v[100:101], 7, v[180:181]
	v_lshl_add_u64 v[100:101], v[98:99], 0, v[100:101]
	v_ashrrev_i32_e32 v179, 31, v178
	global_load_dwordx4 v[134:137], v[100:101], off
	global_load_dwordx4 v[130:133], v[100:101], off offset:64
	v_lshlrev_b64 v[100:101], 7, v[178:179]
	v_lshl_add_u64 v[100:101], v[98:99], 0, v[100:101]
	v_ashrrev_i32_e32 v177, 31, v176
	global_load_dwordx4 v[126:129], v[100:101], off
	global_load_dwordx4 v[122:125], v[100:101], off offset:64
	v_lshlrev_b64 v[100:101], 7, v[176:177]
	v_lshl_add_u64 v[100:101], v[98:99], 0, v[100:101]
	v_ashrrev_i32_e32 v175, 31, v174
	global_load_dwordx4 v[118:121], v[100:101], off
	global_load_dwordx4 v[114:117], v[100:101], off offset:64
	v_lshlrev_b64 v[100:101], 7, v[174:175]
	v_lshl_add_u64 v[100:101], v[98:99], 0, v[100:101]
	v_ashrrev_i32_e32 v173, 31, v172
	global_load_dwordx4 v[110:113], v[100:101], off
	global_load_dwordx4 v[106:109], v[100:101], off offset:64
	v_lshlrev_b64 v[100:101], 7, v[172:173]
	v_lshl_add_u64 v[98:99], v[98:99], 0, v[100:101]
	global_load_dwordx4 v[102:105], v[98:99], off
	s_nop 0
	global_load_dwordx4 v[98:101], v[98:99], off offset:64
	s_waitcnt vmcnt(0)
